# v13 + tail GEMM K-loops hand-scheduled: same k-step order per wave, up to 4 k-steps (32 loads) in flight, no redundant clamped loads
# speedup vs baseline: 1.0210x; 1.0190x over previous
; #define TG_LOAD(A_, B_, KS_) do { const int ks_ = (KS_) < nks ? (KS_) : w; _Pragma("unroll") for (int i = 0; i < 4; ++i) { A_[i] = *(const bf16x8*)(ap + (size_t)i * 16 * K + ks_ * 32); B_[i] = *(const bf16x8*)(bp + (size_t)i * 16 * K + ks_ * 32); } } while (0)
; #define TG_MMA(A_, B_) do { _Pragma("unroll") for (int i = 0; i < 4; ++i) _Pragma("unroll") for (int j = 0; j < 4; ++j) acc[i][j] = __builtin_amdgcn_mfma_f32_16x16x32_bf16(A_[i], B_[j], acc[i][j], 0, 0, 0); } while (0)
; template <int EPI> __device__ __forceinline__ void tail_gemm(LAS unsigned char* lds, const bf16* Am, const bf16* Bt, int K, const TailEpi& E, int tid_in) {
;     ...
;     const bf16* ap = Am + (size_t)(row0 + l15) * K + q4 * 8;
;     const bf16* bp = Bt + (size_t)(col0 + l15) * K + q4 * 8;
;     {
;         const int nks = K / 32;
;         bf16x8 a0[4], b0[4], a1[4], b1[4], a2[4], b2[4];
;     ...
;         TG_LOAD(a0, b0, w); TG_LOAD(a1, b1, w + 8);
;         for (int ks = w; ks < nks; ks += 24) {
;             TG_LOAD(a2, b2, ks + 16); TG_MMA(a0, b0);
;             if (ks + 8 < nks) { TG_LOAD(a0, b0, ks + 24); TG_MMA(a1, b1); }
;             if (ks + 16 < nks) { TG_LOAD(a1, b1, ks + 32); TG_MMA(a2, b2); }
;         }
.LBB0_1316:
	s_lshl_b32 s1, s0, 2
	v_mov_b32_e32 v80, v81
	s_andn2_b32 s1, s1, 63
	s_lshl_b32 s2, s0, 6
	v_mov_b32_e32 v82, v81
	v_mov_b32_e32 v83, v81
	v_mov_b64_e32 v[4:5], v[80:81]
	v_mov_b64_e32 v[0:1], v[80:81]
	v_mov_b64_e32 v[20:21], v[80:81]
	v_mov_b64_e32 v[16:17], v[80:81]
	v_mov_b64_e32 v[36:37], v[80:81]
	v_mov_b64_e32 v[32:33], v[80:81]
	v_mov_b64_e32 v[52:53], v[80:81]
	v_mov_b64_e32 v[48:49], v[80:81]
	v_mov_b64_e32 v[60:61], v[80:81]
	v_mov_b64_e32 v[56:57], v[80:81]
	s_waitcnt vmcnt(0)
	v_mov_b64_e32 v[44:45], v[80:81]
	v_mov_b64_e32 v[40:41], v[80:81]
	v_mov_b64_e32 v[28:29], v[80:81]
	v_mov_b64_e32 v[24:25], v[80:81]
	v_mov_b64_e32 v[12:13], v[80:81]
	v_mov_b64_e32 v[8:9], v[80:81]
	s_addk_i32 s1, 0x4000
	s_and_b32 s12, s2, 0x3c0
	v_mov_b64_e32 v[6:7], v[82:83]
	v_mov_b64_e32 v[2:3], v[82:83]
	v_mov_b64_e32 v[22:23], v[82:83]
	v_mov_b64_e32 v[18:19], v[82:83]
	v_mov_b64_e32 v[38:39], v[82:83]
	v_mov_b64_e32 v[34:35], v[82:83]
	v_mov_b64_e32 v[54:55], v[82:83]
	v_mov_b64_e32 v[50:51], v[82:83]
	v_mov_b64_e32 v[62:63], v[82:83]
	v_mov_b64_e32 v[58:59], v[82:83]
	v_mov_b64_e32 v[46:47], v[82:83]
	v_mov_b64_e32 v[42:43], v[82:83]
	v_mov_b64_e32 v[30:31], v[82:83]
	v_mov_b64_e32 v[26:27], v[82:83]
	v_mov_b64_e32 v[14:15], v[82:83]
	v_mov_b64_e32 v[10:11], v[82:83]
	s_and_saveexec_b64 s[2:3], s[38:39]
	s_cbranch_execz .LBB0_1315
	v_or_b32_e32 v0, s1, v177
	v_ashrrev_i32_e32 v1, 31, v0
	v_lshlrev_b64 v[0:1], 10, v[0:1]
	v_lshl_add_u64 v[172:173], v[164:165], 0, v[0:1]
	v_or_b32_e32 v0, s12, v177
	v_lshlrev_b32_e32 v80, 10, v0
	v_lshl_add_u64 v[174:175], v[166:167], 0, v[80:81]
	v_lshlrev_b32_e32 v80, 6, v176
	v_lshl_add_u64 v[172:173], v[172:173], 0, v[80:81]
	v_lshl_add_u64 v[174:175], v[174:175], 0, v[80:81]
	s_mov_b64 s[40:41], 0x4000
	v_mov_b32_e32 v80, v225
	v_lshl_add_u64 v[186:187], v[172:173], 0, s[40:41]
	v_lshl_add_u64 v[188:189], v[174:175], 0, s[40:41]
	v_lshl_add_u64 v[202:203], v[186:187], 0, s[40:41]
	v_lshl_add_u64 v[228:229], v[188:189], 0, s[40:41]
	v_lshl_add_u64 v[234:235], v[202:203], 0, s[40:41]
	v_lshl_add_u64 v[82:83], v[228:229], 0, s[40:41]
	global_load_dwordx4 v[64:67], v[172:173], off
	global_load_dwordx4 v[68:71], v[174:175], off
	global_load_dwordx4 v[72:75], v[186:187], off
	global_load_dwordx4 v[76:79], v[188:189], off
	global_load_dwordx4 v[84:87], v[202:203], off
	global_load_dwordx4 v[88:91], v[228:229], off
	global_load_dwordx4 v[92:95], v[234:235], off
	global_load_dwordx4 v[96:99], v[82:83], off
	global_load_dwordx4 v[100:103], v[172:173], off offset:512
	global_load_dwordx4 v[104:107], v[174:175], off offset:512
	global_load_dwordx4 v[108:111], v[186:187], off offset:512
	global_load_dwordx4 v[112:115], v[188:189], off offset:512
	global_load_dwordx4 v[116:119], v[202:203], off offset:512
	global_load_dwordx4 v[120:123], v[228:229], off offset:512
	global_load_dwordx4 v[124:127], v[234:235], off offset:512
	global_load_dwordx4 v[128:131], v[82:83], off offset:512
	s_waitcnt vmcnt(8)
	v_mfma_f32_16x16x32_bf16 v[60:63], v[64:67], v[68:71], v[60:63]
	v_mfma_f32_16x16x32_bf16 v[56:59], v[64:67], v[76:79], v[56:59]
	v_mfma_f32_16x16x32_bf16 v[44:47], v[64:67], v[88:91], v[44:47]
	v_mfma_f32_16x16x32_bf16 v[40:43], v[64:67], v[96:99], v[40:43]
	v_mfma_f32_16x16x32_bf16 v[28:31], v[72:75], v[68:71], v[28:31]
	v_mfma_f32_16x16x32_bf16 v[24:27], v[72:75], v[76:79], v[24:27]
	v_mfma_f32_16x16x32_bf16 v[12:15], v[72:75], v[88:91], v[12:15]
	v_mfma_f32_16x16x32_bf16 v[8:11], v[72:75], v[96:99], v[8:11]
	v_mfma_f32_16x16x32_bf16 v[48:51], v[84:87], v[68:71], v[48:51]
	v_mfma_f32_16x16x32_bf16 v[52:55], v[84:87], v[76:79], v[52:55]
	v_mfma_f32_16x16x32_bf16 v[32:35], v[84:87], v[88:91], v[32:35]
	v_mfma_f32_16x16x32_bf16 v[36:39], v[84:87], v[96:99], v[36:39]
	v_mfma_f32_16x16x32_bf16 v[16:19], v[92:95], v[68:71], v[16:19]
	v_mfma_f32_16x16x32_bf16 v[20:23], v[92:95], v[76:79], v[20:23]
	v_mfma_f32_16x16x32_bf16 v[0:3], v[92:95], v[88:91], v[0:3]
	v_mfma_f32_16x16x32_bf16 v[4:7], v[92:95], v[96:99], v[4:7]
	s_waitcnt vmcnt(0)
	v_mfma_f32_16x16x32_bf16 v[60:63], v[100:103], v[104:107], v[60:63]
	v_mfma_f32_16x16x32_bf16 v[56:59], v[100:103], v[112:115], v[56:59]
	v_mfma_f32_16x16x32_bf16 v[44:47], v[100:103], v[120:123], v[44:47]
	v_mfma_f32_16x16x32_bf16 v[40:43], v[100:103], v[128:131], v[40:43]
	v_mfma_f32_16x16x32_bf16 v[28:31], v[108:111], v[104:107], v[28:31]
	v_mfma_f32_16x16x32_bf16 v[24:27], v[108:111], v[112:115], v[24:27]
	v_mfma_f32_16x16x32_bf16 v[12:15], v[108:111], v[120:123], v[12:15]
	v_mfma_f32_16x16x32_bf16 v[8:11], v[108:111], v[128:131], v[8:11]
	v_mfma_f32_16x16x32_bf16 v[48:51], v[116:119], v[104:107], v[48:51]
	v_mfma_f32_16x16x32_bf16 v[52:55], v[116:119], v[112:115], v[52:55]
	v_mfma_f32_16x16x32_bf16 v[32:35], v[116:119], v[120:123], v[32:35]
	v_mfma_f32_16x16x32_bf16 v[36:39], v[116:119], v[128:131], v[36:39]
	v_mfma_f32_16x16x32_bf16 v[16:19], v[124:127], v[104:107], v[16:19]
	v_mfma_f32_16x16x32_bf16 v[20:23], v[124:127], v[112:115], v[20:23]
	v_mfma_f32_16x16x32_bf16 v[0:3], v[124:127], v[120:123], v[0:3]
	v_mfma_f32_16x16x32_bf16 v[4:7], v[124:127], v[128:131], v[4:7]
	v_mov_b32_e32 v225, v80
	v_mov_b32_e32 v82, v81
	v_mov_b32_e32 v83, v81
	s_branch .LBB0_1315

; #define TG_LOAD(A_, B_, KS_) do { const int ks_ = (KS_) < nks ? (KS_) : w; _Pragma("unroll") for (int i = 0; i < 4; ++i) { A_[i] = *(const bf16x8*)(ap + (size_t)i * 16 * K + ks_ * 32); B_[i] = *(const bf16x8*)(bp + (size_t)i * 16 * K + ks_ * 32); } } while (0)
; #define TG_MMA(A_, B_) do { _Pragma("unroll") for (int i = 0; i < 4; ++i) _Pragma("unroll") for (int j = 0; j < 4; ++j) acc[i][j] = __builtin_amdgcn_mfma_f32_16x16x32_bf16(A_[i], B_[j], acc[i][j], 0, 0, 0); } while (0)
; template <int EPI> __device__ __forceinline__ void tail_gemm(LAS unsigned char* lds, const bf16* Am, const bf16* Bt, int K, const TailEpi& E, int tid_in) {
;     ...
;     const int tid = tid_in, lane = tid & 63, w = tid >> 6, l15 = lane & 15, q4 = lane >> 4;
;     const int row0 = MAIN_ROWS + (su >> 4) * 64, col0 = (su & 15) * 64;
;     f32x4 acc[4][4];
; #pragma unroll
;     for (int i = 0; i < 4; ++i)
; #pragma unroll
;         for (int j = 0; j < 4; ++j) acc[i][j] = (f32x4){0.f, 0.f, 0.f, 0.f};
;     const bf16* ap = Am + (size_t)(row0 + l15) * K + q4 * 8;
;     const bf16* bp = Bt + (size_t)(col0 + l15) * K + q4 * 8;
;     {
;         const int nks = K / 32;
;         bf16x8 a0[4], b0[4], a1[4], b1[4], a2[4], b2[4];
;     ...
;         TG_LOAD(a0, b0, w); TG_LOAD(a1, b1, w + 8);
;         for (int ks = w; ks < nks; ks += 24) {
;             TG_LOAD(a2, b2, ks + 16); TG_MMA(a0, b0);
;             if (ks + 8 < nks) { TG_LOAD(a0, b0, ks + 24); TG_MMA(a1, b1); }
;             if (ks + 16 < nks) { TG_LOAD(a1, b1, ks + 32); TG_MMA(a2, b2); }
;         }
.LBB0_1351:
	s_lshl_b32 s1, s0, 2
	v_mov_b32_e32 v80, v81
	s_andn2_b32 s1, s1, 63
	s_lshl_b32 s2, s0, 6
	v_mov_b32_e32 v82, v81
	v_mov_b32_e32 v83, v81
	v_mov_b64_e32 v[4:5], v[80:81]
	v_mov_b64_e32 v[0:1], v[80:81]
	v_mov_b64_e32 v[20:21], v[80:81]
	v_mov_b64_e32 v[16:17], v[80:81]
	v_mov_b64_e32 v[36:37], v[80:81]
	v_mov_b64_e32 v[32:33], v[80:81]
	v_mov_b64_e32 v[52:53], v[80:81]
	v_mov_b64_e32 v[48:49], v[80:81]
	v_mov_b64_e32 v[60:61], v[80:81]
	v_mov_b64_e32 v[56:57], v[80:81]
	s_waitcnt vmcnt(0)
	v_mov_b64_e32 v[44:45], v[80:81]
	v_mov_b64_e32 v[40:41], v[80:81]
	v_mov_b64_e32 v[28:29], v[80:81]
	v_mov_b64_e32 v[24:25], v[80:81]
	v_mov_b64_e32 v[12:13], v[80:81]
	v_mov_b64_e32 v[8:9], v[80:81]
	s_addk_i32 s1, 0x4000
	s_and_b32 s12, s2, 0x3c0
	v_mov_b64_e32 v[6:7], v[82:83]
	v_mov_b64_e32 v[2:3], v[82:83]
	v_mov_b64_e32 v[22:23], v[82:83]
	v_mov_b64_e32 v[18:19], v[82:83]
	v_mov_b64_e32 v[38:39], v[82:83]
	v_mov_b64_e32 v[34:35], v[82:83]
	v_mov_b64_e32 v[54:55], v[82:83]
	v_mov_b64_e32 v[50:51], v[82:83]
	v_mov_b64_e32 v[62:63], v[82:83]
	v_mov_b64_e32 v[58:59], v[82:83]
	v_mov_b64_e32 v[46:47], v[82:83]
	v_mov_b64_e32 v[42:43], v[82:83]
	v_mov_b64_e32 v[30:31], v[82:83]
	v_mov_b64_e32 v[26:27], v[82:83]
	v_mov_b64_e32 v[14:15], v[82:83]
	v_mov_b64_e32 v[10:11], v[82:83]
	s_and_saveexec_b64 s[2:3], s[38:39]
	s_cbranch_execz .LBB0_1350
	v_or_b32_e32 v0, s1, v177
	v_ashrrev_i32_e32 v1, 31, v0
	v_lshlrev_b64 v[0:1], 11, v[0:1]
	v_lshl_add_u64 v[172:173], v[164:165], 0, v[0:1]
	v_or_b32_e32 v0, s12, v177
	v_lshlrev_b32_e32 v80, 11, v0
	v_lshl_add_u64 v[174:175], v[166:167], 0, v[80:81]
	v_lshlrev_b32_e32 v80, 6, v176
	v_lshl_add_u64 v[172:173], v[172:173], 0, v[80:81]
	v_lshl_add_u64 v[174:175], v[174:175], 0, v[80:81]
	s_mov_b64 s[40:41], 0x8000
	v_mov_b32_e32 v80, v225
	v_lshl_add_u64 v[186:187], v[172:173], 0, s[40:41]
	v_lshl_add_u64 v[188:189], v[174:175], 0, s[40:41]
	v_lshl_add_u64 v[202:203], v[186:187], 0, s[40:41]
	v_lshl_add_u64 v[228:229], v[188:189], 0, s[40:41]
	v_lshl_add_u64 v[234:235], v[202:203], 0, s[40:41]
	v_lshl_add_u64 v[82:83], v[228:229], 0, s[40:41]
	global_load_dwordx4 v[64:67], v[172:173], off
	global_load_dwordx4 v[68:71], v[174:175], off
	global_load_dwordx4 v[72:75], v[186:187], off
	global_load_dwordx4 v[76:79], v[188:189], off
	global_load_dwordx4 v[84:87], v[202:203], off
	global_load_dwordx4 v[88:91], v[228:229], off
	global_load_dwordx4 v[92:95], v[234:235], off
	global_load_dwordx4 v[96:99], v[82:83], off
	global_load_dwordx4 v[100:103], v[172:173], off offset:512
	global_load_dwordx4 v[104:107], v[174:175], off offset:512
	global_load_dwordx4 v[108:111], v[186:187], off offset:512
	global_load_dwordx4 v[112:115], v[188:189], off offset:512
	global_load_dwordx4 v[116:119], v[202:203], off offset:512
	global_load_dwordx4 v[120:123], v[228:229], off offset:512
	global_load_dwordx4 v[124:127], v[234:235], off offset:512
	global_load_dwordx4 v[128:131], v[82:83], off offset:512
	global_load_dwordx4 v[132:135], v[172:173], off offset:1024
	global_load_dwordx4 v[136:139], v[174:175], off offset:1024
	global_load_dwordx4 v[140:143], v[186:187], off offset:1024
	global_load_dwordx4 v[144:147], v[188:189], off offset:1024
	global_load_dwordx4 v[148:151], v[202:203], off offset:1024
	global_load_dwordx4 v[152:155], v[228:229], off offset:1024
	global_load_dwordx4 v[156:159], v[234:235], off offset:1024
	global_load_dwordx4 v[160:163], v[82:83], off offset:1024
	global_load_dwordx4 v[204:207], v[172:173], off offset:1536
	global_load_dwordx4 v[208:211], v[174:175], off offset:1536
	global_load_dwordx4 v[212:215], v[186:187], off offset:1536
	global_load_dwordx4 v[224:227], v[188:189], off offset:1536
	global_load_dwordx4 v[236:239], v[202:203], off offset:1536
	global_load_dwordx4 v[240:243], v[228:229], off offset:1536
	global_load_dwordx4 v[244:247], v[234:235], off offset:1536
	global_load_dwordx4 v[248:251], v[82:83], off offset:1536
	s_waitcnt vmcnt(24)
; #define TG_LOAD(A_, B_, KS_) do { const int ks_ = (KS_) < nks ? (KS_) : w; _Pragma("unroll") for (int i = 0; i < 4; ++i) { A_[i] = *(const bf16x8*)(ap + (size_t)i * 16 * K + ks_ * 32); B_[i] = *(const bf16x8*)(bp + (size_t)i * 16 * K + ks_ * 32); } } while (0)
; #define TG_MMA(A_, B_) do { _Pragma("unroll") for (int i = 0; i < 4; ++i) _Pragma("unroll") for (int j = 0; j < 4; ++j) acc[i][j] = __builtin_amdgcn_mfma_f32_16x16x32_bf16(A_[i], B_[j], acc[i][j], 0, 0, 0); } while (0)
; template <int EPI> __device__ __forceinline__ void tail_gemm(LAS unsigned char* lds, const bf16* Am, const bf16* Bt, int K, const TailEpi& E, int tid_in) {
;     ...
;         TG_LOAD(a0, b0, w); TG_LOAD(a1, b1, w + 8);
;         for (int ks = w; ks < nks; ks += 24) {
;             TG_LOAD(a2, b2, ks + 16); TG_MMA(a0, b0);
;             if (ks + 8 < nks) { TG_LOAD(a0, b0, ks + 24); TG_MMA(a1, b1); }
;             if (ks + 16 < nks) { TG_LOAD(a1, b1, ks + 32); TG_MMA(a2, b2); }
;         }
	v_mfma_f32_16x16x32_bf16 v[60:63], v[64:67], v[68:71], v[60:63]
	v_mfma_f32_16x16x32_bf16 v[56:59], v[64:67], v[76:79], v[56:59]
	v_mfma_f32_16x16x32_bf16 v[44:47], v[64:67], v[88:91], v[44:47]
	v_mfma_f32_16x16x32_bf16 v[40:43], v[64:67], v[96:99], v[40:43]
	v_mfma_f32_16x16x32_bf16 v[28:31], v[72:75], v[68:71], v[28:31]
	v_mfma_f32_16x16x32_bf16 v[24:27], v[72:75], v[76:79], v[24:27]
	v_mfma_f32_16x16x32_bf16 v[12:15], v[72:75], v[88:91], v[12:15]
	v_mfma_f32_16x16x32_bf16 v[8:11], v[72:75], v[96:99], v[8:11]
	v_mfma_f32_16x16x32_bf16 v[48:51], v[84:87], v[68:71], v[48:51]
	v_mfma_f32_16x16x32_bf16 v[52:55], v[84:87], v[76:79], v[52:55]
	v_mfma_f32_16x16x32_bf16 v[32:35], v[84:87], v[88:91], v[32:35]
	v_mfma_f32_16x16x32_bf16 v[36:39], v[84:87], v[96:99], v[36:39]
	v_mfma_f32_16x16x32_bf16 v[16:19], v[92:95], v[68:71], v[16:19]
	v_mfma_f32_16x16x32_bf16 v[20:23], v[92:95], v[76:79], v[20:23]
	v_mfma_f32_16x16x32_bf16 v[0:3], v[92:95], v[88:91], v[0:3]
	v_mfma_f32_16x16x32_bf16 v[4:7], v[92:95], v[96:99], v[4:7]
	s_waitcnt vmcnt(16)
	v_mfma_f32_16x16x32_bf16 v[60:63], v[100:103], v[104:107], v[60:63]
	v_mfma_f32_16x16x32_bf16 v[56:59], v[100:103], v[112:115], v[56:59]
	v_mfma_f32_16x16x32_bf16 v[44:47], v[100:103], v[120:123], v[44:47]
	v_mfma_f32_16x16x32_bf16 v[40:43], v[100:103], v[128:131], v[40:43]
	v_mfma_f32_16x16x32_bf16 v[28:31], v[108:111], v[104:107], v[28:31]
	v_mfma_f32_16x16x32_bf16 v[24:27], v[108:111], v[112:115], v[24:27]
	v_mfma_f32_16x16x32_bf16 v[12:15], v[108:111], v[120:123], v[12:15]
	v_mfma_f32_16x16x32_bf16 v[8:11], v[108:111], v[128:131], v[8:11]
	v_mfma_f32_16x16x32_bf16 v[48:51], v[116:119], v[104:107], v[48:51]
	v_mfma_f32_16x16x32_bf16 v[52:55], v[116:119], v[112:115], v[52:55]
	v_mfma_f32_16x16x32_bf16 v[32:35], v[116:119], v[120:123], v[32:35]
	v_mfma_f32_16x16x32_bf16 v[36:39], v[116:119], v[128:131], v[36:39]
	v_mfma_f32_16x16x32_bf16 v[16:19], v[124:127], v[104:107], v[16:19]
	v_mfma_f32_16x16x32_bf16 v[20:23], v[124:127], v[112:115], v[20:23]
	v_mfma_f32_16x16x32_bf16 v[0:3], v[124:127], v[120:123], v[0:3]
	v_mfma_f32_16x16x32_bf16 v[4:7], v[124:127], v[128:131], v[4:7]
	s_waitcnt vmcnt(8)
	v_mfma_f32_16x16x32_bf16 v[60:63], v[132:135], v[136:139], v[60:63]
	v_mfma_f32_16x16x32_bf16 v[56:59], v[132:135], v[144:147], v[56:59]
	v_mfma_f32_16x16x32_bf16 v[44:47], v[132:135], v[152:155], v[44:47]
	v_mfma_f32_16x16x32_bf16 v[40:43], v[132:135], v[160:163], v[40:43]
	v_mfma_f32_16x16x32_bf16 v[28:31], v[140:143], v[136:139], v[28:31]
	v_mfma_f32_16x16x32_bf16 v[24:27], v[140:143], v[144:147], v[24:27]
	v_mfma_f32_16x16x32_bf16 v[12:15], v[140:143], v[152:155], v[12:15]
	v_mfma_f32_16x16x32_bf16 v[8:11], v[140:143], v[160:163], v[8:11]
	v_mfma_f32_16x16x32_bf16 v[48:51], v[148:151], v[136:139], v[48:51]
	v_mfma_f32_16x16x32_bf16 v[52:55], v[148:151], v[144:147], v[52:55]
	v_mfma_f32_16x16x32_bf16 v[32:35], v[148:151], v[152:155], v[32:35]
	v_mfma_f32_16x16x32_bf16 v[36:39], v[148:151], v[160:163], v[36:39]
	v_mfma_f32_16x16x32_bf16 v[16:19], v[156:159], v[136:139], v[16:19]
	v_mfma_f32_16x16x32_bf16 v[20:23], v[156:159], v[144:147], v[20:23]
	v_mfma_f32_16x16x32_bf16 v[0:3], v[156:159], v[152:155], v[0:3]
	v_mfma_f32_16x16x32_bf16 v[4:7], v[156:159], v[160:163], v[4:7]
	s_waitcnt vmcnt(0)
	v_mfma_f32_16x16x32_bf16 v[60:63], v[204:207], v[208:211], v[60:63]
	v_mfma_f32_16x16x32_bf16 v[56:59], v[204:207], v[224:227], v[56:59]
	v_mfma_f32_16x16x32_bf16 v[44:47], v[204:207], v[240:243], v[44:47]
	v_mfma_f32_16x16x32_bf16 v[40:43], v[204:207], v[248:251], v[40:43]
	v_mfma_f32_16x16x32_bf16 v[28:31], v[212:215], v[208:211], v[28:31]
	v_mfma_f32_16x16x32_bf16 v[24:27], v[212:215], v[224:227], v[24:27]
	v_mfma_f32_16x16x32_bf16 v[12:15], v[212:215], v[240:243], v[12:15]
	v_mfma_f32_16x16x32_bf16 v[8:11], v[212:215], v[248:251], v[8:11]
	v_mfma_f32_16x16x32_bf16 v[48:51], v[236:239], v[208:211], v[48:51]
	v_mfma_f32_16x16x32_bf16 v[52:55], v[236:239], v[224:227], v[52:55]
	v_mfma_f32_16x16x32_bf16 v[32:35], v[236:239], v[240:243], v[32:35]
	v_mfma_f32_16x16x32_bf16 v[36:39], v[236:239], v[248:251], v[36:39]
	v_mfma_f32_16x16x32_bf16 v[16:19], v[244:247], v[208:211], v[16:19]
	v_mfma_f32_16x16x32_bf16 v[20:23], v[244:247], v[224:227], v[20:23]
	v_mfma_f32_16x16x32_bf16 v[0:3], v[244:247], v[240:243], v[0:3]
	v_mfma_f32_16x16x32_bf16 v[4:7], v[244:247], v[248:251], v[4:7]
	v_mov_b32_e32 v225, v80
	v_mov_b32_e32 v82, v81
	v_mov_b32_e32 v83, v81
	s_branch .LBB0_1350

; template <int EPI> __device__ __forceinline__ void tail_gemm(LAS unsigned char* lds, const bf16* Am, const bf16* Bt, int K, const TailEpi& E, int tid_in) {
;     ...
;     const int tid = tid_in, lane = tid & 63, w = tid >> 6, l15 = lane & 15, q4 = lane >> 4;
;     const int row0 = MAIN_ROWS + (su >> 4) * 64, col0 = (su & 15) * 64;
;     f32x4 acc[4][4];
; #pragma unroll
;     for (int i = 0; i < 4; ++i)
; #pragma unroll
;         for (int j = 0; j < 4; ++j) acc[i][j] = (f32x4){0.f, 0.f, 0.f, 0.f};
.LBB0_1520:
	s_lshl_b32 s0, s12, 2
	v_mov_b32_e32 v80, v81
	s_and_b32 s1, s0, 0xffffffc0
	s_and_b32 s13, s12, 15
	v_mov_b32_e32 v82, v81
	v_mov_b32_e32 v83, v81
	s_waitcnt lgkmcnt(0)
	v_mov_b64_e32 v[4:5], v[80:81]
	v_mov_b64_e32 v[0:1], v[80:81]
	v_mov_b64_e32 v[20:21], v[80:81]
	v_mov_b64_e32 v[16:17], v[80:81]
	v_mov_b64_e32 v[36:37], v[80:81]
	v_mov_b64_e32 v[32:33], v[80:81]
	v_mov_b64_e32 v[52:53], v[80:81]
	v_mov_b64_e32 v[48:49], v[80:81]
	v_mov_b64_e32 v[60:61], v[80:81]
	v_mov_b64_e32 v[56:57], v[80:81]
	s_waitcnt vmcnt(0)
	v_mov_b64_e32 v[44:45], v[80:81]
	v_mov_b64_e32 v[40:41], v[80:81]
	v_mov_b64_e32 v[28:29], v[80:81]
	v_mov_b64_e32 v[24:25], v[80:81]
	v_mov_b64_e32 v[12:13], v[80:81]
	v_mov_b64_e32 v[8:9], v[80:81]
	s_addk_i32 s1, 0x4000
	s_lshl_b32 s0, s13, 6
	v_mov_b64_e32 v[6:7], v[82:83]
	v_mov_b64_e32 v[2:3], v[82:83]
	v_mov_b64_e32 v[22:23], v[82:83]
	v_mov_b64_e32 v[18:19], v[82:83]
	v_mov_b64_e32 v[38:39], v[82:83]
	v_mov_b64_e32 v[34:35], v[82:83]
	v_mov_b64_e32 v[54:55], v[82:83]
	v_mov_b64_e32 v[50:51], v[82:83]
	v_mov_b64_e32 v[62:63], v[82:83]
	v_mov_b64_e32 v[58:59], v[82:83]
	v_mov_b64_e32 v[46:47], v[82:83]
	v_mov_b64_e32 v[42:43], v[82:83]
	v_mov_b64_e32 v[30:31], v[82:83]
	v_mov_b64_e32 v[26:27], v[82:83]
	v_mov_b64_e32 v[14:15], v[82:83]
	v_mov_b64_e32 v[10:11], v[82:83]
	s_and_saveexec_b64 s[4:5], s[38:39]
	s_cbranch_execz .LBB0_1528
; #define TG_LOAD(A_, B_, KS_) do { const int ks_ = (KS_) < nks ? (KS_) : w; _Pragma("unroll") for (int i = 0; i < 4; ++i) { A_[i] = *(const bf16x8*)(ap + (size_t)i * 16 * K + ks_ * 32); B_[i] = *(const bf16x8*)(bp + (size_t)i * 16 * K + ks_ * 32); } } while (0)
; #define TG_MMA(A_, B_) do { _Pragma("unroll") for (int i = 0; i < 4; ++i) _Pragma("unroll") for (int j = 0; j < 4; ++j) acc[i][j] = __builtin_amdgcn_mfma_f32_16x16x32_bf16(A_[i], B_[j], acc[i][j], 0, 0, 0); } while (0)
; template <int EPI> __device__ __forceinline__ void tail_gemm(LAS unsigned char* lds, const bf16* Am, const bf16* Bt, int K, const TailEpi& E, int tid_in) {
;     ...
;     const bf16* ap = Am + (size_t)(row0 + l15) * K + q4 * 8;
;     const bf16* bp = Bt + (size_t)(col0 + l15) * K + q4 * 8;
;     {
;         const int nks = K / 32;
;         bf16x8 a0[4], b0[4], a1[4], b1[4], a2[4], b2[4];
;     ...
;         TG_LOAD(a0, b0, w); TG_LOAD(a1, b1, w + 8);
;         for (int ks = w; ks < nks; ks += 24) {
;             TG_LOAD(a2, b2, ks + 16); TG_MMA(a0, b0);
;             if (ks + 8 < nks) { TG_LOAD(a0, b0, ks + 24); TG_MMA(a1, b1); }
;             if (ks + 16 < nks) { TG_LOAD(a1, b1, ks + 32); TG_MMA(a2, b2); }
;         }
	v_or_b32_e32 v0, s1, v177
	v_ashrrev_i32_e32 v1, 31, v0
	v_lshlrev_b64 v[0:1], 11, v[0:1]
	v_lshl_add_u64 v[172:173], v[164:165], 0, v[0:1]
	v_or_b32_e32 v0, s0, v177
	v_lshlrev_b32_e32 v80, 11, v0
	v_lshl_add_u64 v[174:175], v[166:167], 0, v[80:81]
	v_lshlrev_b32_e32 v80, 6, v176
	v_lshl_add_u64 v[172:173], v[172:173], 0, v[80:81]
	v_lshl_add_u64 v[174:175], v[174:175], 0, v[80:81]
	s_mov_b64 s[42:43], 0x8000
	v_mov_b32_e32 v80, v225
	v_lshl_add_u64 v[186:187], v[172:173], 0, s[42:43]
	v_lshl_add_u64 v[188:189], v[174:175], 0, s[42:43]
	v_lshl_add_u64 v[202:203], v[186:187], 0, s[42:43]
	v_lshl_add_u64 v[228:229], v[188:189], 0, s[42:43]
	v_lshl_add_u64 v[234:235], v[202:203], 0, s[42:43]
	v_lshl_add_u64 v[82:83], v[228:229], 0, s[42:43]
	global_load_dwordx4 v[64:67], v[172:173], off
	global_load_dwordx4 v[68:71], v[174:175], off
	global_load_dwordx4 v[72:75], v[186:187], off
	global_load_dwordx4 v[76:79], v[188:189], off
	global_load_dwordx4 v[84:87], v[202:203], off
	global_load_dwordx4 v[88:91], v[228:229], off
	global_load_dwordx4 v[92:95], v[234:235], off
	global_load_dwordx4 v[96:99], v[82:83], off
	global_load_dwordx4 v[100:103], v[172:173], off offset:512
	global_load_dwordx4 v[104:107], v[174:175], off offset:512
	global_load_dwordx4 v[108:111], v[186:187], off offset:512
	global_load_dwordx4 v[112:115], v[188:189], off offset:512
	global_load_dwordx4 v[116:119], v[202:203], off offset:512
	global_load_dwordx4 v[120:123], v[228:229], off offset:512
	global_load_dwordx4 v[124:127], v[234:235], off offset:512
	global_load_dwordx4 v[128:131], v[82:83], off offset:512
	global_load_dwordx4 v[132:135], v[172:173], off offset:1024
	global_load_dwordx4 v[136:139], v[174:175], off offset:1024
	global_load_dwordx4 v[140:143], v[186:187], off offset:1024
	global_load_dwordx4 v[144:147], v[188:189], off offset:1024
	global_load_dwordx4 v[148:151], v[202:203], off offset:1024
	global_load_dwordx4 v[152:155], v[228:229], off offset:1024
	global_load_dwordx4 v[156:159], v[234:235], off offset:1024
	global_load_dwordx4 v[160:163], v[82:83], off offset:1024
	global_load_dwordx4 v[204:207], v[172:173], off offset:1536
	global_load_dwordx4 v[208:211], v[174:175], off offset:1536
	global_load_dwordx4 v[212:215], v[186:187], off offset:1536
	global_load_dwordx4 v[224:227], v[188:189], off offset:1536
	global_load_dwordx4 v[236:239], v[202:203], off offset:1536
	global_load_dwordx4 v[240:243], v[228:229], off offset:1536
	global_load_dwordx4 v[244:247], v[234:235], off offset:1536
	global_load_dwordx4 v[248:251], v[82:83], off offset:1536
	s_waitcnt vmcnt(24)
	v_mfma_f32_16x16x32_bf16 v[60:63], v[64:67], v[68:71], v[60:63]
	v_mfma_f32_16x16x32_bf16 v[56:59], v[64:67], v[76:79], v[56:59]
	v_mfma_f32_16x16x32_bf16 v[44:47], v[64:67], v[88:91], v[44:47]
	v_mfma_f32_16x16x32_bf16 v[40:43], v[64:67], v[96:99], v[40:43]
	v_mfma_f32_16x16x32_bf16 v[28:31], v[72:75], v[68:71], v[28:31]
	v_mfma_f32_16x16x32_bf16 v[24:27], v[72:75], v[76:79], v[24:27]
	v_mfma_f32_16x16x32_bf16 v[12:15], v[72:75], v[88:91], v[12:15]
	v_mfma_f32_16x16x32_bf16 v[8:11], v[72:75], v[96:99], v[8:11]
	v_mfma_f32_16x16x32_bf16 v[48:51], v[84:87], v[68:71], v[48:51]
	v_mfma_f32_16x16x32_bf16 v[52:55], v[84:87], v[76:79], v[52:55]
	v_mfma_f32_16x16x32_bf16 v[32:35], v[84:87], v[88:91], v[32:35]
	v_mfma_f32_16x16x32_bf16 v[36:39], v[84:87], v[96:99], v[36:39]
	v_mfma_f32_16x16x32_bf16 v[16:19], v[92:95], v[68:71], v[16:19]
	v_mfma_f32_16x16x32_bf16 v[20:23], v[92:95], v[76:79], v[20:23]
	v_mfma_f32_16x16x32_bf16 v[0:3], v[92:95], v[88:91], v[0:3]
	v_mfma_f32_16x16x32_bf16 v[4:7], v[92:95], v[96:99], v[4:7]
	s_waitcnt vmcnt(16)
	v_mfma_f32_16x16x32_bf16 v[60:63], v[100:103], v[104:107], v[60:63]
	v_mfma_f32_16x16x32_bf16 v[56:59], v[100:103], v[112:115], v[56:59]
	v_mfma_f32_16x16x32_bf16 v[44:47], v[100:103], v[120:123], v[44:47]
	v_mfma_f32_16x16x32_bf16 v[40:43], v[100:103], v[128:131], v[40:43]
	v_mfma_f32_16x16x32_bf16 v[28:31], v[108:111], v[104:107], v[28:31]
	v_mfma_f32_16x16x32_bf16 v[24:27], v[108:111], v[112:115], v[24:27]
	v_mfma_f32_16x16x32_bf16 v[12:15], v[108:111], v[120:123], v[12:15]
	v_mfma_f32_16x16x32_bf16 v[8:11], v[108:111], v[128:131], v[8:11]
	v_mfma_f32_16x16x32_bf16 v[48:51], v[116:119], v[104:107], v[48:51]
	v_mfma_f32_16x16x32_bf16 v[52:55], v[116:119], v[112:115], v[52:55]
	v_mfma_f32_16x16x32_bf16 v[32:35], v[116:119], v[120:123], v[32:35]
	v_mfma_f32_16x16x32_bf16 v[36:39], v[116:119], v[128:131], v[36:39]
	v_mfma_f32_16x16x32_bf16 v[16:19], v[124:127], v[104:107], v[16:19]
	v_mfma_f32_16x16x32_bf16 v[20:23], v[124:127], v[112:115], v[20:23]
	v_mfma_f32_16x16x32_bf16 v[0:3], v[124:127], v[120:123], v[0:3]
	v_mfma_f32_16x16x32_bf16 v[4:7], v[124:127], v[128:131], v[4:7]
	s_waitcnt vmcnt(8)
	v_mfma_f32_16x16x32_bf16 v[60:63], v[132:135], v[136:139], v[60:63]
	v_mfma_f32_16x16x32_bf16 v[56:59], v[132:135], v[144:147], v[56:59]
	v_mfma_f32_16x16x32_bf16 v[44:47], v[132:135], v[152:155], v[44:47]
	v_mfma_f32_16x16x32_bf16 v[40:43], v[132:135], v[160:163], v[40:43]
	v_mfma_f32_16x16x32_bf16 v[28:31], v[140:143], v[136:139], v[28:31]
	v_mfma_f32_16x16x32_bf16 v[24:27], v[140:143], v[144:147], v[24:27]
	v_mfma_f32_16x16x32_bf16 v[12:15], v[140:143], v[152:155], v[12:15]
	v_mfma_f32_16x16x32_bf16 v[8:11], v[140:143], v[160:163], v[8:11]
	v_mfma_f32_16x16x32_bf16 v[48:51], v[148:151], v[136:139], v[48:51]
	v_mfma_f32_16x16x32_bf16 v[52:55], v[148:151], v[144:147], v[52:55]
	v_mfma_f32_16x16x32_bf16 v[32:35], v[148:151], v[152:155], v[32:35]
	v_mfma_f32_16x16x32_bf16 v[36:39], v[148:151], v[160:163], v[36:39]
	v_mfma_f32_16x16x32_bf16 v[16:19], v[156:159], v[136:139], v[16:19]
	v_mfma_f32_16x16x32_bf16 v[20:23], v[156:159], v[144:147], v[20:23]
	v_mfma_f32_16x16x32_bf16 v[0:3], v[156:159], v[152:155], v[0:3]
	v_mfma_f32_16x16x32_bf16 v[4:7], v[156:159], v[160:163], v[4:7]
	s_waitcnt vmcnt(0)
	v_mfma_f32_16x16x32_bf16 v[60:63], v[204:207], v[208:211], v[60:63]
	v_mfma_f32_16x16x32_bf16 v[56:59], v[204:207], v[224:227], v[56:59]
	v_mfma_f32_16x16x32_bf16 v[44:47], v[204:207], v[240:243], v[44:47]
	v_mfma_f32_16x16x32_bf16 v[40:43], v[204:207], v[248:251], v[40:43]
	v_mfma_f32_16x16x32_bf16 v[28:31], v[212:215], v[208:211], v[28:31]
	v_mfma_f32_16x16x32_bf16 v[24:27], v[212:215], v[224:227], v[24:27]
	v_mfma_f32_16x16x32_bf16 v[12:15], v[212:215], v[240:243], v[12:15]
	v_mfma_f32_16x16x32_bf16 v[8:11], v[212:215], v[248:251], v[8:11]
	v_mfma_f32_16x16x32_bf16 v[48:51], v[236:239], v[208:211], v[48:51]
	v_mfma_f32_16x16x32_bf16 v[52:55], v[236:239], v[224:227], v[52:55]
	v_mfma_f32_16x16x32_bf16 v[32:35], v[236:239], v[240:243], v[32:35]
	v_mfma_f32_16x16x32_bf16 v[36:39], v[236:239], v[248:251], v[36:39]
	v_mfma_f32_16x16x32_bf16 v[16:19], v[244:247], v[208:211], v[16:19]
	v_mfma_f32_16x16x32_bf16 v[20:23], v[244:247], v[224:227], v[20:23]
	v_mfma_f32_16x16x32_bf16 v[0:3], v[244:247], v[240:243], v[0:3]
	v_mfma_f32_16x16x32_bf16 v[4:7], v[244:247], v[248:251], v[4:7]
	v_mov_b32_e32 v225, v80
	v_mov_b32_e32 v82, v81
	v_mov_b32_e32 v83, v81

; #define TG_LOAD(A_, B_, KS_) do { const int ks_ = (KS_) < nks ? (KS_) : w; _Pragma("unroll") for (int i = 0; i < 4; ++i) { A_[i] = *(const bf16x8*)(ap + (size_t)i * 16 * K + ks_ * 32); B_[i] = *(const bf16x8*)(bp + (size_t)i * 16 * K + ks_ * 32); } } while (0)
; #define TG_MMA(A_, B_) do { _Pragma("unroll") for (int i = 0; i < 4; ++i) _Pragma("unroll") for (int j = 0; j < 4; ++j) acc[i][j] = __builtin_amdgcn_mfma_f32_16x16x32_bf16(A_[i], B_[j], acc[i][j], 0, 0, 0); } while (0)
; template <int EPI> __device__ __forceinline__ void tail_gemm(LAS unsigned char* lds, const bf16* Am, const bf16* Bt, int K, const TailEpi& E, int tid_in) {
;     ...
;     const int tid = tid_in, lane = tid & 63, w = tid >> 6, l15 = lane & 15, q4 = lane >> 4;
;     const int row0 = MAIN_ROWS + (su >> 4) * 64, col0 = (su & 15) * 64;
;     f32x4 acc[4][4];
; #pragma unroll
;     for (int i = 0; i < 4; ++i)
; #pragma unroll
;         for (int j = 0; j < 4; ++j) acc[i][j] = (f32x4){0.f, 0.f, 0.f, 0.f};
;     const bf16* ap = Am + (size_t)(row0 + l15) * K + q4 * 8;
;     const bf16* bp = Bt + (size_t)(col0 + l15) * K + q4 * 8;
;     {
;         const int nks = K / 32;
;         bf16x8 a0[4], b0[4], a1[4], b1[4], a2[4], b2[4];
;     ...
;         TG_LOAD(a0, b0, w); TG_LOAD(a1, b1, w + 8);
;         for (int ks = w; ks < nks; ks += 24) {
;             TG_LOAD(a2, b2, ks + 16); TG_MMA(a0, b0);
;             if (ks + 8 < nks) { TG_LOAD(a0, b0, ks + 24); TG_MMA(a1, b1); }
;             if (ks + 16 < nks) { TG_LOAD(a1, b1, ks + 32); TG_MMA(a2, b2); }
;         }
.LBB0_1753:
	s_lshl_b32 s0, s12, 2
	v_mov_b32_e32 v80, v81
	s_and_b32 s1, s0, 0xffffffc0
	s_and_b32 s13, s12, 15
	v_mov_b32_e32 v82, v81
	v_mov_b32_e32 v83, v81
	v_mov_b64_e32 v[4:5], v[80:81]
	s_waitcnt lgkmcnt(0)
	v_mov_b64_e32 v[0:1], v[80:81]
	v_mov_b64_e32 v[20:21], v[80:81]
	v_mov_b64_e32 v[16:17], v[80:81]
	v_mov_b64_e32 v[36:37], v[80:81]
	v_mov_b64_e32 v[32:33], v[80:81]
	v_mov_b64_e32 v[52:53], v[80:81]
	v_mov_b64_e32 v[48:49], v[80:81]
	v_mov_b64_e32 v[60:61], v[80:81]
	v_mov_b64_e32 v[56:57], v[80:81]
	s_waitcnt vmcnt(0)
	v_mov_b64_e32 v[44:45], v[80:81]
	v_mov_b64_e32 v[40:41], v[80:81]
	v_mov_b64_e32 v[28:29], v[80:81]
	v_mov_b64_e32 v[24:25], v[80:81]
	v_mov_b64_e32 v[12:13], v[80:81]
	v_mov_b64_e32 v[8:9], v[80:81]
	s_addk_i32 s1, 0x4000
	s_lshl_b32 s0, s13, 6
	v_mov_b64_e32 v[6:7], v[82:83]
	v_mov_b64_e32 v[2:3], v[82:83]
	v_mov_b64_e32 v[22:23], v[82:83]
	v_mov_b64_e32 v[18:19], v[82:83]
	v_mov_b64_e32 v[38:39], v[82:83]
	v_mov_b64_e32 v[34:35], v[82:83]
	v_mov_b64_e32 v[54:55], v[82:83]
	v_mov_b64_e32 v[50:51], v[82:83]
	v_mov_b64_e32 v[62:63], v[82:83]
	v_mov_b64_e32 v[58:59], v[82:83]
	v_mov_b64_e32 v[46:47], v[82:83]
	v_mov_b64_e32 v[42:43], v[82:83]
	v_mov_b64_e32 v[30:31], v[82:83]
	v_mov_b64_e32 v[26:27], v[82:83]
	v_mov_b64_e32 v[14:15], v[82:83]
	v_mov_b64_e32 v[10:11], v[82:83]
	s_and_saveexec_b64 s[2:3], s[36:37]
	s_cbranch_execz .LBB0_1761
	v_or_b32_e32 v0, s1, v177
	v_mad_i64_i32 v[172:173], s[4:5], v0, s92, v[164:165]
	v_or_b32_e32 v0, s0, v177
	v_mul_u32_u24_e32 v0, 0xb00, v0
	v_lshlrev_b32_e32 v80, 1, v0
	v_lshl_add_u64 v[174:175], v[166:167], 0, v[80:81]
	v_lshlrev_b32_e32 v80, 6, v176
	v_lshl_add_u64 v[172:173], v[172:173], 0, v[80:81]
	v_lshl_add_u64 v[174:175], v[174:175], 0, v[80:81]
	s_mov_b64 s[40:41], 0x16000
	v_mov_b32_e32 v80, v225
	v_lshl_add_u64 v[186:187], v[172:173], 0, s[40:41]
	v_lshl_add_u64 v[188:189], v[174:175], 0, s[40:41]
	v_lshl_add_u64 v[202:203], v[186:187], 0, s[40:41]
	v_lshl_add_u64 v[228:229], v[188:189], 0, s[40:41]
	v_lshl_add_u64 v[234:235], v[202:203], 0, s[40:41]
	v_lshl_add_u64 v[82:83], v[228:229], 0, s[40:41]
	global_load_dwordx4 v[64:67], v[172:173], off
	global_load_dwordx4 v[68:71], v[174:175], off
	global_load_dwordx4 v[72:75], v[186:187], off
	global_load_dwordx4 v[76:79], v[188:189], off
	global_load_dwordx4 v[84:87], v[202:203], off
	global_load_dwordx4 v[88:91], v[228:229], off
	global_load_dwordx4 v[92:95], v[234:235], off
	global_load_dwordx4 v[96:99], v[82:83], off
	global_load_dwordx4 v[100:103], v[172:173], off offset:512
	global_load_dwordx4 v[104:107], v[174:175], off offset:512
	global_load_dwordx4 v[108:111], v[186:187], off offset:512
	global_load_dwordx4 v[112:115], v[188:189], off offset:512
	global_load_dwordx4 v[116:119], v[202:203], off offset:512
	global_load_dwordx4 v[120:123], v[228:229], off offset:512
	global_load_dwordx4 v[124:127], v[234:235], off offset:512
	global_load_dwordx4 v[128:131], v[82:83], off offset:512
	global_load_dwordx4 v[132:135], v[172:173], off offset:1024
	global_load_dwordx4 v[136:139], v[174:175], off offset:1024
	global_load_dwordx4 v[140:143], v[186:187], off offset:1024
	global_load_dwordx4 v[144:147], v[188:189], off offset:1024
	global_load_dwordx4 v[148:151], v[202:203], off offset:1024
	global_load_dwordx4 v[152:155], v[228:229], off offset:1024
	global_load_dwordx4 v[156:159], v[234:235], off offset:1024
	global_load_dwordx4 v[160:163], v[82:83], off offset:1024
	global_load_dwordx4 v[204:207], v[172:173], off offset:1536
	global_load_dwordx4 v[208:211], v[174:175], off offset:1536
	global_load_dwordx4 v[212:215], v[186:187], off offset:1536
	global_load_dwordx4 v[224:227], v[188:189], off offset:1536
	global_load_dwordx4 v[236:239], v[202:203], off offset:1536
	global_load_dwordx4 v[240:243], v[228:229], off offset:1536
	global_load_dwordx4 v[244:247], v[234:235], off offset:1536
	global_load_dwordx4 v[248:251], v[82:83], off offset:1536
	s_waitcnt vmcnt(24)
	v_mfma_f32_16x16x32_bf16 v[60:63], v[64:67], v[68:71], v[60:63]
	v_mfma_f32_16x16x32_bf16 v[56:59], v[64:67], v[76:79], v[56:59]
	v_mfma_f32_16x16x32_bf16 v[44:47], v[64:67], v[88:91], v[44:47]
	v_mfma_f32_16x16x32_bf16 v[40:43], v[64:67], v[96:99], v[40:43]
	v_mfma_f32_16x16x32_bf16 v[28:31], v[72:75], v[68:71], v[28:31]
	v_mfma_f32_16x16x32_bf16 v[24:27], v[72:75], v[76:79], v[24:27]
	v_mfma_f32_16x16x32_bf16 v[12:15], v[72:75], v[88:91], v[12:15]
	v_mfma_f32_16x16x32_bf16 v[8:11], v[72:75], v[96:99], v[8:11]
	v_mfma_f32_16x16x32_bf16 v[48:51], v[84:87], v[68:71], v[48:51]
	v_mfma_f32_16x16x32_bf16 v[52:55], v[84:87], v[76:79], v[52:55]
	v_mfma_f32_16x16x32_bf16 v[32:35], v[84:87], v[88:91], v[32:35]
	v_mfma_f32_16x16x32_bf16 v[36:39], v[84:87], v[96:99], v[36:39]
	v_mfma_f32_16x16x32_bf16 v[16:19], v[92:95], v[68:71], v[16:19]
	v_mfma_f32_16x16x32_bf16 v[20:23], v[92:95], v[76:79], v[20:23]
	v_mfma_f32_16x16x32_bf16 v[0:3], v[92:95], v[88:91], v[0:3]
	v_mfma_f32_16x16x32_bf16 v[4:7], v[92:95], v[96:99], v[4:7]
	global_load_dwordx4 v[64:67], v[172:173], off offset:2048
	global_load_dwordx4 v[68:71], v[174:175], off offset:2048
	global_load_dwordx4 v[72:75], v[186:187], off offset:2048
	global_load_dwordx4 v[76:79], v[188:189], off offset:2048
	global_load_dwordx4 v[84:87], v[202:203], off offset:2048
	global_load_dwordx4 v[88:91], v[228:229], off offset:2048
	global_load_dwordx4 v[92:95], v[234:235], off offset:2048
	global_load_dwordx4 v[96:99], v[82:83], off offset:2048
	s_waitcnt vmcnt(24)
; #define TG_LOAD(A_, B_, KS_) do { const int ks_ = (KS_) < nks ? (KS_) : w; _Pragma("unroll") for (int i = 0; i < 4; ++i) { A_[i] = *(const bf16x8*)(ap + (size_t)i * 16 * K + ks_ * 32); B_[i] = *(const bf16x8*)(bp + (size_t)i * 16 * K + ks_ * 32); } } while (0)
; #define TG_MMA(A_, B_) do { _Pragma("unroll") for (int i = 0; i < 4; ++i) _Pragma("unroll") for (int j = 0; j < 4; ++j) acc[i][j] = __builtin_amdgcn_mfma_f32_16x16x32_bf16(A_[i], B_[j], acc[i][j], 0, 0, 0); } while (0)
; template <int EPI> __device__ __forceinline__ void tail_gemm(LAS unsigned char* lds, const bf16* Am, const bf16* Bt, int K, const TailEpi& E, int tid_in) {
;     ...
;         TG_LOAD(a0, b0, w); TG_LOAD(a1, b1, w + 8);
;         for (int ks = w; ks < nks; ks += 24) {
;             TG_LOAD(a2, b2, ks + 16); TG_MMA(a0, b0);
;             if (ks + 8 < nks) { TG_LOAD(a0, b0, ks + 24); TG_MMA(a1, b1); }
;             if (ks + 16 < nks) { TG_LOAD(a1, b1, ks + 32); TG_MMA(a2, b2); }
;         }
	v_mfma_f32_16x16x32_bf16 v[60:63], v[100:103], v[104:107], v[60:63]
	v_mfma_f32_16x16x32_bf16 v[56:59], v[100:103], v[112:115], v[56:59]
	v_mfma_f32_16x16x32_bf16 v[44:47], v[100:103], v[120:123], v[44:47]
	v_mfma_f32_16x16x32_bf16 v[40:43], v[100:103], v[128:131], v[40:43]
	v_mfma_f32_16x16x32_bf16 v[28:31], v[108:111], v[104:107], v[28:31]
	v_mfma_f32_16x16x32_bf16 v[24:27], v[108:111], v[112:115], v[24:27]
	v_mfma_f32_16x16x32_bf16 v[12:15], v[108:111], v[120:123], v[12:15]
	v_mfma_f32_16x16x32_bf16 v[8:11], v[108:111], v[128:131], v[8:11]
	v_mfma_f32_16x16x32_bf16 v[48:51], v[116:119], v[104:107], v[48:51]
	v_mfma_f32_16x16x32_bf16 v[52:55], v[116:119], v[112:115], v[52:55]
	v_mfma_f32_16x16x32_bf16 v[32:35], v[116:119], v[120:123], v[32:35]
	v_mfma_f32_16x16x32_bf16 v[36:39], v[116:119], v[128:131], v[36:39]
	v_mfma_f32_16x16x32_bf16 v[16:19], v[124:127], v[104:107], v[16:19]
	v_mfma_f32_16x16x32_bf16 v[20:23], v[124:127], v[112:115], v[20:23]
	v_mfma_f32_16x16x32_bf16 v[0:3], v[124:127], v[120:123], v[0:3]
	v_mfma_f32_16x16x32_bf16 v[4:7], v[124:127], v[128:131], v[4:7]
	global_load_dwordx4 v[100:103], v[172:173], off offset:2560
	global_load_dwordx4 v[104:107], v[174:175], off offset:2560
	global_load_dwordx4 v[108:111], v[186:187], off offset:2560
	global_load_dwordx4 v[112:115], v[188:189], off offset:2560
	global_load_dwordx4 v[116:119], v[202:203], off offset:2560
	global_load_dwordx4 v[120:123], v[228:229], off offset:2560
	global_load_dwordx4 v[124:127], v[234:235], off offset:2560
	global_load_dwordx4 v[128:131], v[82:83], off offset:2560
	s_waitcnt vmcnt(24)
	v_mfma_f32_16x16x32_bf16 v[60:63], v[132:135], v[136:139], v[60:63]
	v_mfma_f32_16x16x32_bf16 v[56:59], v[132:135], v[144:147], v[56:59]
	v_mfma_f32_16x16x32_bf16 v[44:47], v[132:135], v[152:155], v[44:47]
	v_mfma_f32_16x16x32_bf16 v[40:43], v[132:135], v[160:163], v[40:43]
	v_mfma_f32_16x16x32_bf16 v[28:31], v[140:143], v[136:139], v[28:31]
	v_mfma_f32_16x16x32_bf16 v[24:27], v[140:143], v[144:147], v[24:27]
	v_mfma_f32_16x16x32_bf16 v[12:15], v[140:143], v[152:155], v[12:15]
	v_mfma_f32_16x16x32_bf16 v[8:11], v[140:143], v[160:163], v[8:11]
	v_mfma_f32_16x16x32_bf16 v[48:51], v[148:151], v[136:139], v[48:51]
	v_mfma_f32_16x16x32_bf16 v[52:55], v[148:151], v[144:147], v[52:55]
	v_mfma_f32_16x16x32_bf16 v[32:35], v[148:151], v[152:155], v[32:35]
	v_mfma_f32_16x16x32_bf16 v[36:39], v[148:151], v[160:163], v[36:39]
	v_mfma_f32_16x16x32_bf16 v[16:19], v[156:159], v[136:139], v[16:19]
	v_mfma_f32_16x16x32_bf16 v[20:23], v[156:159], v[144:147], v[20:23]
	v_mfma_f32_16x16x32_bf16 v[0:3], v[156:159], v[152:155], v[0:3]
	v_mfma_f32_16x16x32_bf16 v[4:7], v[156:159], v[160:163], v[4:7]
	global_load_dwordx4 v[132:135], v[172:173], off offset:3072
	global_load_dwordx4 v[136:139], v[174:175], off offset:3072
	global_load_dwordx4 v[140:143], v[186:187], off offset:3072
	global_load_dwordx4 v[144:147], v[188:189], off offset:3072
	global_load_dwordx4 v[148:151], v[202:203], off offset:3072
	global_load_dwordx4 v[152:155], v[228:229], off offset:3072
	global_load_dwordx4 v[156:159], v[234:235], off offset:3072
	global_load_dwordx4 v[160:163], v[82:83], off offset:3072
	s_waitcnt vmcnt(24)
	v_mfma_f32_16x16x32_bf16 v[60:63], v[204:207], v[208:211], v[60:63]
	v_mfma_f32_16x16x32_bf16 v[56:59], v[204:207], v[224:227], v[56:59]
	v_mfma_f32_16x16x32_bf16 v[44:47], v[204:207], v[240:243], v[44:47]
	v_mfma_f32_16x16x32_bf16 v[40:43], v[204:207], v[248:251], v[40:43]
	v_mfma_f32_16x16x32_bf16 v[28:31], v[212:215], v[208:211], v[28:31]
	v_mfma_f32_16x16x32_bf16 v[24:27], v[212:215], v[224:227], v[24:27]
	v_mfma_f32_16x16x32_bf16 v[12:15], v[212:215], v[240:243], v[12:15]
	v_mfma_f32_16x16x32_bf16 v[8:11], v[212:215], v[248:251], v[8:11]
	v_mfma_f32_16x16x32_bf16 v[48:51], v[236:239], v[208:211], v[48:51]
	v_mfma_f32_16x16x32_bf16 v[52:55], v[236:239], v[224:227], v[52:55]
	v_mfma_f32_16x16x32_bf16 v[32:35], v[236:239], v[240:243], v[32:35]
	v_mfma_f32_16x16x32_bf16 v[36:39], v[236:239], v[248:251], v[36:39]
	v_mfma_f32_16x16x32_bf16 v[16:19], v[244:247], v[208:211], v[16:19]
	v_mfma_f32_16x16x32_bf16 v[20:23], v[244:247], v[224:227], v[20:23]
	v_mfma_f32_16x16x32_bf16 v[0:3], v[244:247], v[240:243], v[0:3]
	v_mfma_f32_16x16x32_bf16 v[4:7], v[244:247], v[248:251], v[4:7]
	global_load_dwordx4 v[204:207], v[172:173], off offset:3584
	global_load_dwordx4 v[208:211], v[174:175], off offset:3584
	global_load_dwordx4 v[212:215], v[186:187], off offset:3584
	global_load_dwordx4 v[224:227], v[188:189], off offset:3584
	global_load_dwordx4 v[236:239], v[202:203], off offset:3584
	global_load_dwordx4 v[240:243], v[228:229], off offset:3584
	global_load_dwordx4 v[244:247], v[234:235], off offset:3584
	global_load_dwordx4 v[248:251], v[82:83], off offset:3584
	s_waitcnt vmcnt(24)
; #define TG_LOAD(A_, B_, KS_) do { const int ks_ = (KS_) < nks ? (KS_) : w; _Pragma("unroll") for (int i = 0; i < 4; ++i) { A_[i] = *(const bf16x8*)(ap + (size_t)i * 16 * K + ks_ * 32); B_[i] = *(const bf16x8*)(bp + (size_t)i * 16 * K + ks_ * 32); } } while (0)
; #define TG_MMA(A_, B_) do { _Pragma("unroll") for (int i = 0; i < 4; ++i) _Pragma("unroll") for (int j = 0; j < 4; ++j) acc[i][j] = __builtin_amdgcn_mfma_f32_16x16x32_bf16(A_[i], B_[j], acc[i][j], 0, 0, 0); } while (0)
; template <int EPI> __device__ __forceinline__ void tail_gemm(LAS unsigned char* lds, const bf16* Am, const bf16* Bt, int K, const TailEpi& E, int tid_in) {
;     ...
;         TG_LOAD(a0, b0, w); TG_LOAD(a1, b1, w + 8);
;         for (int ks = w; ks < nks; ks += 24) {
;             TG_LOAD(a2, b2, ks + 16); TG_MMA(a0, b0);
;             if (ks + 8 < nks) { TG_LOAD(a0, b0, ks + 24); TG_MMA(a1, b1); }
;             if (ks + 16 < nks) { TG_LOAD(a1, b1, ks + 32); TG_MMA(a2, b2); }
;         }
	v_mfma_f32_16x16x32_bf16 v[60:63], v[64:67], v[68:71], v[60:63]
	v_mfma_f32_16x16x32_bf16 v[56:59], v[64:67], v[76:79], v[56:59]
	v_mfma_f32_16x16x32_bf16 v[44:47], v[64:67], v[88:91], v[44:47]
	v_mfma_f32_16x16x32_bf16 v[40:43], v[64:67], v[96:99], v[40:43]
	v_mfma_f32_16x16x32_bf16 v[28:31], v[72:75], v[68:71], v[28:31]
	v_mfma_f32_16x16x32_bf16 v[24:27], v[72:75], v[76:79], v[24:27]
	v_mfma_f32_16x16x32_bf16 v[12:15], v[72:75], v[88:91], v[12:15]
	v_mfma_f32_16x16x32_bf16 v[8:11], v[72:75], v[96:99], v[8:11]
	v_mfma_f32_16x16x32_bf16 v[48:51], v[84:87], v[68:71], v[48:51]
	v_mfma_f32_16x16x32_bf16 v[52:55], v[84:87], v[76:79], v[52:55]
	v_mfma_f32_16x16x32_bf16 v[32:35], v[84:87], v[88:91], v[32:35]
	v_mfma_f32_16x16x32_bf16 v[36:39], v[84:87], v[96:99], v[36:39]
	v_mfma_f32_16x16x32_bf16 v[16:19], v[92:95], v[68:71], v[16:19]
	v_mfma_f32_16x16x32_bf16 v[20:23], v[92:95], v[76:79], v[20:23]
	v_mfma_f32_16x16x32_bf16 v[0:3], v[92:95], v[88:91], v[0:3]
	v_mfma_f32_16x16x32_bf16 v[4:7], v[92:95], v[96:99], v[4:7]
	s_mov_b64 s[40:41], 0x1000
	v_lshl_add_u64 v[172:173], v[172:173], 0, s[40:41]
	v_lshl_add_u64 v[174:175], v[174:175], 0, s[40:41]
	v_lshl_add_u64 v[186:187], v[186:187], 0, s[40:41]
	v_lshl_add_u64 v[188:189], v[188:189], 0, s[40:41]
	v_lshl_add_u64 v[202:203], v[202:203], 0, s[40:41]
	v_lshl_add_u64 v[228:229], v[228:229], 0, s[40:41]
	v_lshl_add_u64 v[234:235], v[234:235], 0, s[40:41]
	v_lshl_add_u64 v[82:83], v[82:83], 0, s[40:41]
	global_load_dwordx4 v[64:67], v[172:173], off
	global_load_dwordx4 v[68:71], v[174:175], off
	global_load_dwordx4 v[72:75], v[186:187], off
	global_load_dwordx4 v[76:79], v[188:189], off
	global_load_dwordx4 v[84:87], v[202:203], off
	global_load_dwordx4 v[88:91], v[228:229], off
	global_load_dwordx4 v[92:95], v[234:235], off
	global_load_dwordx4 v[96:99], v[82:83], off
	s_waitcnt vmcnt(24)
	v_mfma_f32_16x16x32_bf16 v[60:63], v[100:103], v[104:107], v[60:63]
	v_mfma_f32_16x16x32_bf16 v[56:59], v[100:103], v[112:115], v[56:59]
	v_mfma_f32_16x16x32_bf16 v[44:47], v[100:103], v[120:123], v[44:47]
	v_mfma_f32_16x16x32_bf16 v[40:43], v[100:103], v[128:131], v[40:43]
	v_mfma_f32_16x16x32_bf16 v[28:31], v[108:111], v[104:107], v[28:31]
	v_mfma_f32_16x16x32_bf16 v[24:27], v[108:111], v[112:115], v[24:27]
	v_mfma_f32_16x16x32_bf16 v[12:15], v[108:111], v[120:123], v[12:15]
	v_mfma_f32_16x16x32_bf16 v[8:11], v[108:111], v[128:131], v[8:11]
	v_mfma_f32_16x16x32_bf16 v[48:51], v[116:119], v[104:107], v[48:51]
	v_mfma_f32_16x16x32_bf16 v[52:55], v[116:119], v[112:115], v[52:55]
	v_mfma_f32_16x16x32_bf16 v[32:35], v[116:119], v[120:123], v[32:35]
	v_mfma_f32_16x16x32_bf16 v[36:39], v[116:119], v[128:131], v[36:39]
	v_mfma_f32_16x16x32_bf16 v[16:19], v[124:127], v[104:107], v[16:19]
	v_mfma_f32_16x16x32_bf16 v[20:23], v[124:127], v[112:115], v[20:23]
	v_mfma_f32_16x16x32_bf16 v[0:3], v[124:127], v[120:123], v[0:3]
	v_mfma_f32_16x16x32_bf16 v[4:7], v[124:127], v[128:131], v[4:7]
	global_load_dwordx4 v[100:103], v[172:173], off offset:512
	global_load_dwordx4 v[104:107], v[174:175], off offset:512
	global_load_dwordx4 v[108:111], v[186:187], off offset:512
	global_load_dwordx4 v[112:115], v[188:189], off offset:512
	global_load_dwordx4 v[116:119], v[202:203], off offset:512
	global_load_dwordx4 v[120:123], v[228:229], off offset:512
	global_load_dwordx4 v[124:127], v[234:235], off offset:512
	global_load_dwordx4 v[128:131], v[82:83], off offset:512
	s_waitcnt vmcnt(24)
	v_mfma_f32_16x16x32_bf16 v[60:63], v[132:135], v[136:139], v[60:63]
	v_mfma_f32_16x16x32_bf16 v[56:59], v[132:135], v[144:147], v[56:59]
	v_mfma_f32_16x16x32_bf16 v[44:47], v[132:135], v[152:155], v[44:47]
	v_mfma_f32_16x16x32_bf16 v[40:43], v[132:135], v[160:163], v[40:43]
	v_mfma_f32_16x16x32_bf16 v[28:31], v[140:143], v[136:139], v[28:31]
	v_mfma_f32_16x16x32_bf16 v[24:27], v[140:143], v[144:147], v[24:27]
	v_mfma_f32_16x16x32_bf16 v[12:15], v[140:143], v[152:155], v[12:15]
	v_mfma_f32_16x16x32_bf16 v[8:11], v[140:143], v[160:163], v[8:11]
	v_mfma_f32_16x16x32_bf16 v[48:51], v[148:151], v[136:139], v[48:51]
	v_mfma_f32_16x16x32_bf16 v[52:55], v[148:151], v[144:147], v[52:55]
	v_mfma_f32_16x16x32_bf16 v[32:35], v[148:151], v[152:155], v[32:35]
	v_mfma_f32_16x16x32_bf16 v[36:39], v[148:151], v[160:163], v[36:39]
	v_mfma_f32_16x16x32_bf16 v[16:19], v[156:159], v[136:139], v[16:19]
	v_mfma_f32_16x16x32_bf16 v[20:23], v[156:159], v[144:147], v[20:23]
	v_mfma_f32_16x16x32_bf16 v[0:3], v[156:159], v[152:155], v[0:3]
	v_mfma_f32_16x16x32_bf16 v[4:7], v[156:159], v[160:163], v[4:7]
	global_load_dwordx4 v[132:135], v[172:173], off offset:1024
	global_load_dwordx4 v[136:139], v[174:175], off offset:1024
	global_load_dwordx4 v[140:143], v[186:187], off offset:1024
	global_load_dwordx4 v[144:147], v[188:189], off offset:1024
	global_load_dwordx4 v[148:151], v[202:203], off offset:1024
	global_load_dwordx4 v[152:155], v[228:229], off offset:1024
	global_load_dwordx4 v[156:159], v[234:235], off offset:1024
	global_load_dwordx4 v[160:163], v[82:83], off offset:1024
	s_waitcnt vmcnt(24)
; #define TG_LOAD(A_, B_, KS_) do { const int ks_ = (KS_) < nks ? (KS_) : w; _Pragma("unroll") for (int i = 0; i < 4; ++i) { A_[i] = *(const bf16x8*)(ap + (size_t)i * 16 * K + ks_ * 32); B_[i] = *(const bf16x8*)(bp + (size_t)i * 16 * K + ks_ * 32); } } while (0)
; #define TG_MMA(A_, B_) do { _Pragma("unroll") for (int i = 0; i < 4; ++i) _Pragma("unroll") for (int j = 0; j < 4; ++j) acc[i][j] = __builtin_amdgcn_mfma_f32_16x16x32_bf16(A_[i], B_[j], acc[i][j], 0, 0, 0); } while (0)
; template <int EPI> __device__ __forceinline__ void tail_gemm(LAS unsigned char* lds, const bf16* Am, const bf16* Bt, int K, const TailEpi& E, int tid_in) {
;     ...
;         TG_LOAD(a0, b0, w); TG_LOAD(a1, b1, w + 8);
;         for (int ks = w; ks < nks; ks += 24) {
;             TG_LOAD(a2, b2, ks + 16); TG_MMA(a0, b0);
;             if (ks + 8 < nks) { TG_LOAD(a0, b0, ks + 24); TG_MMA(a1, b1); }
;             if (ks + 16 < nks) { TG_LOAD(a1, b1, ks + 32); TG_MMA(a2, b2); }
;         }
	v_mfma_f32_16x16x32_bf16 v[60:63], v[204:207], v[208:211], v[60:63]
	v_mfma_f32_16x16x32_bf16 v[56:59], v[204:207], v[224:227], v[56:59]
	v_mfma_f32_16x16x32_bf16 v[44:47], v[204:207], v[240:243], v[44:47]
	v_mfma_f32_16x16x32_bf16 v[40:43], v[204:207], v[248:251], v[40:43]
	v_mfma_f32_16x16x32_bf16 v[28:31], v[212:215], v[208:211], v[28:31]
	v_mfma_f32_16x16x32_bf16 v[24:27], v[212:215], v[224:227], v[24:27]
	v_mfma_f32_16x16x32_bf16 v[12:15], v[212:215], v[240:243], v[12:15]
	v_mfma_f32_16x16x32_bf16 v[8:11], v[212:215], v[248:251], v[8:11]
	v_mfma_f32_16x16x32_bf16 v[48:51], v[236:239], v[208:211], v[48:51]
	v_mfma_f32_16x16x32_bf16 v[52:55], v[236:239], v[224:227], v[52:55]
	v_mfma_f32_16x16x32_bf16 v[32:35], v[236:239], v[240:243], v[32:35]
	v_mfma_f32_16x16x32_bf16 v[36:39], v[236:239], v[248:251], v[36:39]
	v_mfma_f32_16x16x32_bf16 v[16:19], v[244:247], v[208:211], v[16:19]
	v_mfma_f32_16x16x32_bf16 v[20:23], v[244:247], v[224:227], v[20:23]
	v_mfma_f32_16x16x32_bf16 v[0:3], v[244:247], v[240:243], v[0:3]
	v_mfma_f32_16x16x32_bf16 v[4:7], v[244:247], v[248:251], v[4:7]
	s_waitcnt vmcnt(16)
	v_mfma_f32_16x16x32_bf16 v[60:63], v[64:67], v[68:71], v[60:63]
	v_mfma_f32_16x16x32_bf16 v[56:59], v[64:67], v[76:79], v[56:59]
	v_mfma_f32_16x16x32_bf16 v[44:47], v[64:67], v[88:91], v[44:47]
	v_mfma_f32_16x16x32_bf16 v[40:43], v[64:67], v[96:99], v[40:43]
	v_mfma_f32_16x16x32_bf16 v[28:31], v[72:75], v[68:71], v[28:31]
	v_mfma_f32_16x16x32_bf16 v[24:27], v[72:75], v[76:79], v[24:27]
	v_mfma_f32_16x16x32_bf16 v[12:15], v[72:75], v[88:91], v[12:15]
	v_mfma_f32_16x16x32_bf16 v[8:11], v[72:75], v[96:99], v[8:11]
	v_mfma_f32_16x16x32_bf16 v[48:51], v[84:87], v[68:71], v[48:51]
	v_mfma_f32_16x16x32_bf16 v[52:55], v[84:87], v[76:79], v[52:55]
	v_mfma_f32_16x16x32_bf16 v[32:35], v[84:87], v[88:91], v[32:35]
	v_mfma_f32_16x16x32_bf16 v[36:39], v[84:87], v[96:99], v[36:39]
	v_mfma_f32_16x16x32_bf16 v[16:19], v[92:95], v[68:71], v[16:19]
	v_mfma_f32_16x16x32_bf16 v[20:23], v[92:95], v[76:79], v[20:23]
	v_mfma_f32_16x16x32_bf16 v[0:3], v[92:95], v[88:91], v[0:3]
	v_mfma_f32_16x16x32_bf16 v[4:7], v[92:95], v[96:99], v[4:7]
	s_waitcnt vmcnt(8)
	v_mfma_f32_16x16x32_bf16 v[60:63], v[100:103], v[104:107], v[60:63]
	v_mfma_f32_16x16x32_bf16 v[56:59], v[100:103], v[112:115], v[56:59]
	v_mfma_f32_16x16x32_bf16 v[44:47], v[100:103], v[120:123], v[44:47]
	v_mfma_f32_16x16x32_bf16 v[40:43], v[100:103], v[128:131], v[40:43]
	v_mfma_f32_16x16x32_bf16 v[28:31], v[108:111], v[104:107], v[28:31]
	v_mfma_f32_16x16x32_bf16 v[24:27], v[108:111], v[112:115], v[24:27]
	v_mfma_f32_16x16x32_bf16 v[12:15], v[108:111], v[120:123], v[12:15]
	v_mfma_f32_16x16x32_bf16 v[8:11], v[108:111], v[128:131], v[8:11]
	v_mfma_f32_16x16x32_bf16 v[48:51], v[116:119], v[104:107], v[48:51]
	v_mfma_f32_16x16x32_bf16 v[52:55], v[116:119], v[112:115], v[52:55]
	v_mfma_f32_16x16x32_bf16 v[32:35], v[116:119], v[120:123], v[32:35]
	v_mfma_f32_16x16x32_bf16 v[36:39], v[116:119], v[128:131], v[36:39]
	v_mfma_f32_16x16x32_bf16 v[16:19], v[124:127], v[104:107], v[16:19]
	v_mfma_f32_16x16x32_bf16 v[20:23], v[124:127], v[112:115], v[20:23]
	v_mfma_f32_16x16x32_bf16 v[0:3], v[124:127], v[120:123], v[0:3]
	v_mfma_f32_16x16x32_bf16 v[4:7], v[124:127], v[128:131], v[4:7]
	s_waitcnt vmcnt(0)
	v_mfma_f32_16x16x32_bf16 v[60:63], v[132:135], v[136:139], v[60:63]
	v_mfma_f32_16x16x32_bf16 v[56:59], v[132:135], v[144:147], v[56:59]
	v_mfma_f32_16x16x32_bf16 v[44:47], v[132:135], v[152:155], v[44:47]
	v_mfma_f32_16x16x32_bf16 v[40:43], v[132:135], v[160:163], v[40:43]
	v_mfma_f32_16x16x32_bf16 v[28:31], v[140:143], v[136:139], v[28:31]
	v_mfma_f32_16x16x32_bf16 v[24:27], v[140:143], v[144:147], v[24:27]
	v_mfma_f32_16x16x32_bf16 v[12:15], v[140:143], v[152:155], v[12:15]
	v_mfma_f32_16x16x32_bf16 v[8:11], v[140:143], v[160:163], v[8:11]
	v_mfma_f32_16x16x32_bf16 v[48:51], v[148:151], v[136:139], v[48:51]
	v_mfma_f32_16x16x32_bf16 v[52:55], v[148:151], v[144:147], v[52:55]
	v_mfma_f32_16x16x32_bf16 v[32:35], v[148:151], v[152:155], v[32:35]
	v_mfma_f32_16x16x32_bf16 v[36:39], v[148:151], v[160:163], v[36:39]
	v_mfma_f32_16x16x32_bf16 v[16:19], v[156:159], v[136:139], v[16:19]
	v_mfma_f32_16x16x32_bf16 v[20:23], v[156:159], v[144:147], v[20:23]
	v_mfma_f32_16x16x32_bf16 v[0:3], v[156:159], v[152:155], v[0:3]
	v_mfma_f32_16x16x32_bf16 v[4:7], v[156:159], v[160:163], v[4:7]
	v_mov_b32_e32 v225, v80
	v_mov_b32_e32 v82, v81
	v_mov_b32_e32 v83, v81
